# prep_rows row loop software-pipelined: next row's loads issued into staging registers before the current row is processed
# baseline (speedup 1.0000x reference)
; __device__ __forceinline__ unsigned cvtpk(float lo, float hi) { typedef __bf16 bf2 __attribute__((ext_vector_type(2))); f32x2 v = {lo, hi}; bf2 b = __builtin_convertvector(v, bf2); return __builtin_bit_cast(unsigned, b); }
; __device__ __forceinline__ bf16_t tobf(float f) { return (bf16_t)(cvtpk(f, 0.f) & 0xffffu); }
; __device__ __forceinline__ void prep_rows(bf16_t* proj, const float* gq, const float* gk, const float* mq, const float* mkv, const float* rope, int gw, int NGW, int lane) {
;     const int j = lane & 15; const bool up = (lane & 16) != 0;
;     for (int row = gw; row < NTOK; row += NGW) {
;         bf16_t* pr = proj + (size_t)row * LDP; const int l = row & (SEQL - 1); const int pos = (lane < 32) ? (l >> 6) : (l & 63);
;         const f32x2 cs = *(const f32x2*)(rope + ((size_t)pos * 16 + j) * 2);
;         float hv[10];
; #pragma unroll
;         for (int hh = 0; hh < 10; ++hh) hv[hh] = bf1(pr[(hh < 8 ? C_BQ + hh * 64 : C_BK + (hh - 8) * 64) + lane]);
;         const float ggq = gq[lane], ggk = gk[lane];
; #pragma unroll
;         for (int hh = 0; hh < 10; ++hh) {
;             const int base = hh < 8 ? C_BQ + hh * 64 : C_BK + (hh - 8) * 64; const float gg = hh < 8 ? ggq : ggk;
;             float v = hv[hh]; const float ss = wave_sum(v * v);
;             v = v * __builtin_amdgcn_rsqf(ss * (1.f / 64) + EPSN) * gg;
;             const float pv = __shfl_xor(v, 16);
;             const float o = up ? (pv * cs[1] + v * cs[0]) : (v * cs[0] - pv * cs[1]);
;             pr[base + lane] = tobf(o);
;         }
;         {
;             const u32x2 w = *(const u32x2*)(pr + C_CQ + 4 * lane); f32x4 v = {bflo(w.x), bfhi(w.x), bflo(w.y), bfhi(w.y)};
;             const float rs = __builtin_amdgcn_rsqf(wave_sum((v[0] * v[0] + v[1] * v[1]) + (v[2] * v[2] + v[3] * v[3])) * (1.f / 256) + EPSN); const f32x4 gg = ((const f32x4*)mq)[lane];
;             u32x2 o; o.x = cvtpk(v[0] * rs * gg[0], v[1] * rs * gg[1]); o.y = cvtpk(v[2] * rs * gg[2], v[3] * rs * gg[3]); *(u32x2*)(pr + C_CQ + 4 * lane) = o;
;         }
;         {
;             const unsigned w = *(const unsigned*)(pr + C_CKV + 2 * lane); const float a = bflo(w), b = bfhi(w);
;             const float rs = __builtin_amdgcn_rsqf(wave_sum(a * a + b * b) * (1.f / 128) + EPSN); const f32x2 gg = ((const f32x2*)mkv)[lane];
.LBB0_260:
	s_cmp_lt_i32 s24, 3
	s_cselect_b64 s[4:5], -1, 0
	s_cmp_gt_i32 s25, 2
	s_cselect_b64 s[6:7], -1, 0
	s_and_b64 s[4:5], s[4:5], s[6:7]
	s_andn2_b64 vcc, exec, s[4:5]
	s_cbranch_vccnz .LBB0_352
	s_mov_b64 s[34:35], s[0:1]
	s_load_dwordx2 s[36:37], s[34:35], 0x118
	v_mov_b32_e32 v30, v1
	s_lshl_b32 s10, s33, 3
	v_readfirstlane_b32 s3, v30
	s_ashr_i32 s27, s3, 6
	v_and_b32_e32 v38, 63, v30
	s_add_i32 s3, s27, s10
	v_and_b32_e32 v31, 16, v30
	s_cmpk_gt_i32 s3, 0x3fff
	v_cmp_gt_u32_e32 vcc, 32, v38
	v_lshlrev_b32_e32 v2, 1, v38
	v_lshlrev_b32_e32 v4, 4, v38
	v_lshlrev_b32_e32 v40, 3, v38
	s_cbranch_scc1 .LBB0_266
	v_mbcnt_lo_u32_b32 v3, -1, 0
	v_mbcnt_hi_u32_b32 v3, -1, v3
	v_and_b32_e32 v5, 64, v3
	v_add_u32_e32 v5, 64, v5
	v_xor_b32_e32 v12, 1, v3
	v_cmp_lt_i32_e64 s[6:7], v12, v5
	s_waitcnt lgkmcnt(0)
	s_add_u32 s8, s36, 0xf800000
	s_addc_u32 s9, s37, 0
	v_cndmask_b32_e64 v12, v3, v12, s[6:7]
	v_lshlrev_b32_e32 v32, 2, v12
	v_xor_b32_e32 v12, 2, v3
	v_cmp_lt_i32_e64 s[6:7], v12, v5
	s_load_dwordx8 s[16:23], s[34:35], 0x60
	v_mov_b32_e32 v7, 0
	v_cndmask_b32_e64 v12, v3, v12, s[6:7]
	v_lshlrev_b32_e32 v33, 2, v12
	v_xor_b32_e32 v12, 4, v3
	v_cmp_lt_i32_e64 s[6:7], v12, v5
	v_and_b32_e32 v22, 30, v2
	v_lshrrev_b32_e32 v16, 4, v38
	v_cndmask_b32_e64 v12, v3, v12, s[6:7]
	v_lshlrev_b32_e32 v34, 2, v12
	v_xor_b32_e32 v12, 8, v3
	v_cmp_lt_i32_e64 s[6:7], v12, v5
	v_lshlrev_b32_e32 v6, 2, v38
	v_mov_b32_e32 v41, v7
	v_cndmask_b32_e64 v12, v3, v12, s[6:7]
	v_lshlrev_b32_e32 v35, 2, v12
	v_xor_b32_e32 v12, 16, v3
	v_cmp_lt_i32_e64 s[6:7], v12, v5
	v_add_u32_e32 v16, v16, v22
	v_mov_b32_e32 v18, 0x1500
	v_cndmask_b32_e64 v12, v3, v12, s[6:7]
	v_lshlrev_b32_e32 v36, 2, v12
	v_xor_b32_e32 v12, 32, v3
	v_cmp_lt_i32_e64 s[6:7], v12, v5
	v_mov_b32_e32 v5, v7
	v_cmp_eq_u32_e64 s[4:5], 0, v31
	v_cndmask_b32_e64 v3, v3, v12, s[6:7]
	s_ashr_i32 s6, s27, 31
	s_ashr_i32 s7, s10, 31
	s_add_u32 s10, s27, s10
	s_addc_u32 s6, s6, s7
	s_mulk_i32 s6, 0x1940
	s_mul_hi_u32 s7, s10, 0x1940
	s_add_i32 s7, s7, s6
	s_mulk_i32 s10, 0x1940
	s_waitcnt lgkmcnt(0)
	v_lshl_add_u64 v[12:13], s[20:21], 0, v[4:5]
	v_and_b32_e32 v5, 31, v30
	s_add_u32 s10, s36, s10
	v_lshl_add_u64 v[8:9], s[16:17], 0, v[6:7]
	v_lshl_add_u64 v[10:11], s[18:19], 0, v[6:7]
	v_lshlrev_b32_e32 v37, 2, v3
	v_mov_b32_e32 v3, v7
	v_lshl_add_u64 v[14:15], s[22:23], 0, v[40:41]
	v_lshl_or_b32 v16, v16, 1, v18
	v_mov_b32_e32 v17, v7
	s_addc_u32 s11, s37, s7
	s_mul_hi_i32 s16, s26, 0x1940
	s_mul_i32 s17, s26, 0x1940
	v_lshl_or_b32 v18, v5, 1, v18
	v_mov_b32_e32 v19, v7
	v_or_b32_e32 v6, 0x1400, v6
	v_or_b32_e32 v20, 0x1200, v40
	v_mov_b32_e32 v21, v7
	v_lshlrev_b32_e32 v5, 2, v22
	s_movk_i32 s18, 0x1000
	v_mov_b32_e32 v39, 0x358637bd
	s_mov_b32 s19, s3
	global_load_dwordx4 v[124:127], v[12:13], off
	global_load_dwordx2 v[128:129], v[14:15], off
	global_load_dword v148, v[8:9], off
	global_load_dword v149, v[10:11], off
	v_lshl_add_u64 v[150:151], s[10:11], 0, v[2:3]
	global_load_ushort v130, v[150:151], off offset:3072
	global_load_ushort v131, v[150:151], off offset:3200
	global_load_ushort v132, v[150:151], off offset:3328
	global_load_ushort v133, v[150:151], off offset:3456
	global_load_ushort v134, v[150:151], off offset:3584
	global_load_ushort v135, v[150:151], off offset:3712
	global_load_ushort v136, v[150:151], off offset:3840
	global_load_ushort v137, v[150:151], off offset:3968
	v_add_co_u32_e64 v152, s[6:7], s18, v150
	s_nop 0
	v_addc_co_u32_e64 v153, s[6:7], 0, v151, s[6:7]
	global_load_ushort v138, v[152:153], off
	global_load_ushort v139, v[152:153], off offset:128
	v_lshl_add_u64 v[152:153], s[10:11], 0, v[20:21]
	global_load_dwordx2 v[140:141], v[152:153], off
	v_lshl_add_u64 v[152:153], s[10:11], 0, v[6:7]
	global_load_dword v142, v[152:153], off
	v_lshl_add_u64 v[152:153], s[10:11], 0, v[18:19]
	global_load_ushort v143, v[152:153], off
	s_bfe_u32 s6, s19, 0x60006
	s_and_b32 s7, s19, 63
	v_mov_b32_e32 v152, s7
	v_mov_b32_e32 v153, s6
	v_cndmask_b32_e32 v152, v152, v153, vcc
	v_lshl_or_b32 v152, v152, 7, v5
	global_load_dwordx2 v[144:145], v152, s[8:9]
	s_and_saveexec_b64 s[98:99], vcc
	s_and_b32 s100, s19, 0xfff
	v_lshl_or_b32 v152, s100, 7, v5
	global_load_dwordx2 v[146:147], v152, s[8:9]
	s_or_b64 exec, exec, s[98:99]
	s_branch .LBB0_264

; __device__ __forceinline__ bf16_t tobf(float f) { return (bf16_t)(cvtpk(f, 0.f) & 0xffffu); }
; __device__ __forceinline__ void prep_rows(bf16_t* proj, const float* gq, const float* gk, const float* mq, const float* mkv, const float* rope, int gw, int NGW, int lane) {
;     ...
;     for (int row = gw; row < NTOK; row += NGW) {
;         bf16_t* pr = proj + (size_t)row * LDP; const int l = row & (SEQL - 1); const int pos = (lane < 32) ? (l >> 6) : (l & 63);
;         const f32x2 cs = *(const f32x2*)(rope + ((size_t)pos * 16 + j) * 2);
;         float hv[10];
; #pragma unroll
;         for (int hh = 0; hh < 10; ++hh) hv[hh] = bf1(pr[(hh < 8 ? C_BQ + hh * 64 : C_BK + (hh - 8) * 64) + lane]);
;         const float ggq = gq[lane], ggk = gk[lane];
; #pragma unroll
;         for (int hh = 0; hh < 10; ++hh) {
;             const int base = hh < 8 ? C_BQ + hh * 64 : C_BK + (hh - 8) * 64; const float gg = hh < 8 ? ggq : ggk;
;             float v = hv[hh]; const float ss = wave_sum(v * v);
;             v = v * __builtin_amdgcn_rsqf(ss * (1.f / 64) + EPSN) * gg;
;             const float pv = __shfl_xor(v, 16);
;             const float o = up ? (pv * cs[1] + v * cs[0]) : (v * cs[0] - pv * cs[1]);
;             pr[base + lane] = tobf(o);
;         }
.LBB0_264:
	s_waitcnt lgkmcnt(0)
	s_waitcnt vmcnt(0)
	v_mov_b32_e32 v43, v130
	v_mov_b32_e32 v48, v131
	v_mov_b32_e32 v49, v132
	v_mov_b32_e32 v50, v133
	v_mov_b32_e32 v51, v134
	v_mov_b32_e32 v52, v135
	v_mov_b32_e32 v53, v136
	v_mov_b32_e32 v54, v137
	v_mov_b32_e32 v55, v138
	v_mov_b32_e32 v56, v139
	v_mov_b32_e32 v46, v140
	v_mov_b32_e32 v47, v141
	v_mov_b32_e32 v58, v142
	v_mov_b32_e32 v59, v143
	v_mov_b32_e32 v44, v144
	v_mov_b32_e32 v45, v145
	v_mov_b32_e32 v120, v146
	v_mov_b32_e32 v121, v147
	v_mov_b32_e32 v42, v148
	v_mov_b32_e32 v41, v149
	v_lshl_add_u64 v[22:23], s[10:11], 0, v[2:3]
	v_add_co_u32_e64 v24, s[6:7], s18, v22
	v_lshl_add_u64 v[26:27], s[10:11], 0, v[20:21]
	s_nop 0
	v_addc_co_u32_e64 v25, s[6:7], 0, v23, s[6:7]
	v_lshl_add_u64 v[28:29], s[10:11], 0, v[6:7]
	s_add_i32 s101, s19, s26
	s_cmpk_lt_i32 s101, 0x4000
	s_cbranch_scc0 .Lpp0_nopf
	s_add_u32 s96, s10, s17
	s_addc_u32 s97, s11, s16
	v_lshl_add_u64 v[150:151], s[96:97], 0, v[2:3]
	global_load_ushort v130, v[150:151], off offset:3072
	global_load_ushort v131, v[150:151], off offset:3200
	global_load_ushort v132, v[150:151], off offset:3328
	global_load_ushort v133, v[150:151], off offset:3456
	global_load_ushort v134, v[150:151], off offset:3584
	global_load_ushort v135, v[150:151], off offset:3712
	global_load_ushort v136, v[150:151], off offset:3840
	global_load_ushort v137, v[150:151], off offset:3968
	v_add_co_u32_e64 v152, s[6:7], s18, v150
	s_nop 0
	v_addc_co_u32_e64 v153, s[6:7], 0, v151, s[6:7]
	global_load_ushort v138, v[152:153], off
	global_load_ushort v139, v[152:153], off offset:128
	v_lshl_add_u64 v[152:153], s[96:97], 0, v[20:21]
	global_load_dwordx2 v[140:141], v[152:153], off
	v_lshl_add_u64 v[152:153], s[96:97], 0, v[6:7]
	global_load_dword v142, v[152:153], off
	v_lshl_add_u64 v[152:153], s[96:97], 0, v[18:19]
	global_load_ushort v143, v[152:153], off
	s_bfe_u32 s6, s101, 0x60006
	s_and_b32 s7, s101, 63
	v_mov_b32_e32 v152, s7
	v_mov_b32_e32 v153, s6
	v_cndmask_b32_e32 v152, v152, v153, vcc
	v_lshl_or_b32 v152, v152, 7, v5
	global_load_dwordx2 v[144:145], v152, s[8:9]
	s_and_saveexec_b64 s[98:99], vcc
	s_and_b32 s100, s101, 0xfff
	v_lshl_or_b32 v152, s100, 7, v5
	global_load_dwordx2 v[146:147], v152, s[8:9]
	s_or_b64 exec, exec, s[98:99]
.Lpp0_nopf:
	v_lshlrev_b32_e32 v43, 16, v43
	v_lshlrev_b32_e32 v48, 16, v48
	v_mul_f32_e32 v57, v43, v43
	v_mul_f32_e32 v60, v48, v48
	ds_bpermute_b32 v57, v32, v57
	ds_bpermute_b32 v60, v32, v60
	v_lshlrev_b32_e32 v49, 16, v49
	v_mul_f32_e32 v61, v49, v49
	ds_bpermute_b32 v61, v32, v61
	s_waitcnt lgkmcnt(2)
	v_fmac_f32_e32 v57, v43, v43
	s_waitcnt lgkmcnt(1)
	v_fmac_f32_e32 v60, v48, v48
	ds_bpermute_b32 v64, v33, v57
	ds_bpermute_b32 v65, v33, v60
	s_waitcnt lgkmcnt(2)
	v_fmac_f32_e32 v61, v49, v49
	ds_bpermute_b32 v66, v33, v61
	v_lshlrev_b32_e32 v50, 16, v50
	s_waitcnt lgkmcnt(2)
	v_add_f32_e32 v57, v57, v64
	s_waitcnt lgkmcnt(1)
	v_add_f32_e32 v60, v60, v65
	ds_bpermute_b32 v64, v34, v57
	ds_bpermute_b32 v65, v34, v60
	v_mul_f32_e32 v62, v50, v50
	s_waitcnt lgkmcnt(2)
	v_add_f32_e32 v61, v61, v66
	ds_bpermute_b32 v62, v32, v62
	s_waitcnt lgkmcnt(2)
	v_add_f32_e32 v57, v57, v64
	s_waitcnt lgkmcnt(1)
	v_add_f32_e32 v60, v60, v65
	ds_bpermute_b32 v64, v35, v57
	ds_bpermute_b32 v66, v34, v61
	ds_bpermute_b32 v65, v35, v60
	s_waitcnt lgkmcnt(3)
	v_fmac_f32_e32 v62, v50, v50
	ds_bpermute_b32 v67, v33, v62
	s_waitcnt lgkmcnt(3)
	v_add_f32_e32 v57, v57, v64
	s_waitcnt lgkmcnt(2)
	v_add_f32_e32 v61, v61, v66
	s_waitcnt lgkmcnt(1)
	v_add_f32_e32 v60, v60, v65
	ds_bpermute_b32 v64, v36, v57
	ds_bpermute_b32 v66, v35, v61
	ds_bpermute_b32 v65, v36, v60
	v_lshlrev_b32_e32 v51, 16, v51
	v_mul_f32_e32 v63, v51, v51
	ds_bpermute_b32 v63, v32, v63
	s_waitcnt lgkmcnt(3)
	v_add_f32_e32 v57, v57, v64
	v_add_f32_e32 v62, v62, v67
	s_waitcnt lgkmcnt(2)
	v_add_f32_e32 v61, v61, v66
	s_waitcnt lgkmcnt(1)
	v_add_f32_e32 v60, v60, v65
	ds_bpermute_b32 v64, v37, v57
	ds_bpermute_b32 v67, v34, v62
	ds_bpermute_b32 v66, v36, v61
	ds_bpermute_b32 v65, v37, v60
	s_waitcnt lgkmcnt(4)
	v_fmac_f32_e32 v63, v51, v51
	ds_bpermute_b32 v68, v33, v63
	s_waitcnt lgkmcnt(4)
	v_add_f32_e32 v57, v57, v64
	s_waitcnt lgkmcnt(3)
	v_add_f32_e32 v62, v62, v67
	s_waitcnt lgkmcnt(2)
	v_add_f32_e32 v61, v61, v66
	s_waitcnt lgkmcnt(1)
	v_add_f32_e32 v60, v60, v65
	v_fmamk_f32 v57, v57, 0x3c800000, v39
	ds_bpermute_b32 v67, v35, v62
	ds_bpermute_b32 v66, v37, v61
	v_fmamk_f32 v60, v60, 0x3c800000, v39
	v_rsq_f32_e32 v57, v57
	v_rsq_f32_e32 v60, v60
	s_waitcnt lgkmcnt(2)
	v_add_f32_e32 v63, v63, v68
	ds_bpermute_b32 v68, v34, v63
	v_mul_f32_e32 v43, v57, v43
	s_waitcnt lgkmcnt(2)
	v_add_f32_e32 v62, v62, v67
	s_waitcnt lgkmcnt(1)
	v_add_f32_e32 v61, v61, v66
	v_mul_f32_e32 v48, v60, v48
	v_mul_f32_e32 v43, v42, v43
	ds_bpermute_b32 v67, v36, v62
	v_fmamk_f32 v61, v61, 0x3c800000, v39
	v_mul_f32_e32 v48, v42, v48
	ds_bpermute_b32 v57, v36, v43
	v_rsq_f32_e32 v61, v61
	ds_bpermute_b32 v60, v36, v48
	s_waitcnt lgkmcnt(3)
	v_add_f32_e32 v63, v63, v68
	ds_bpermute_b32 v68, v35, v63
	s_waitcnt lgkmcnt(3)
	v_add_f32_e32 v62, v62, v67
	v_mul_f32_e32 v49, v61, v49
	s_waitcnt lgkmcnt(2)
	v_mul_f32_e32 v57, v45, v57
	ds_bpermute_b32 v67, v37, v62
	v_mul_f32_e32 v49, v42, v49
	s_waitcnt lgkmcnt(2)
	v_mul_f32_e32 v60, v45, v60
	v_cndmask_b32_e64 v57, v57, -v57, s[4:5]
	ds_bpermute_b32 v61, v36, v49
	v_cndmask_b32_e64 v60, v60, -v60, s[4:5]
	v_fmac_f32_e32 v57, v44, v43
	v_lshlrev_b32_e32 v52, 16, v52
	v_fmac_f32_e32 v60, v44, v48
	v_cvt_pk_bf16_f32 v43, v57, s0
	s_waitcnt lgkmcnt(2)
; __device__ __forceinline__ bf16_t tobf(float f) { return (bf16_t)(cvtpk(f, 0.f) & 0xffffu); }
; __device__ __forceinline__ void prep_rows(bf16_t* proj, const float* gq, const float* gk, const float* mq, const float* mkv, const float* rope, int gw, int NGW, int lane) {
;     ...
;         for (int hh = 0; hh < 10; ++hh) {
;             const int base = hh < 8 ? C_BQ + hh * 64 : C_BK + (hh - 8) * 64; const float gg = hh < 8 ? ggq : ggk;
;             float v = hv[hh]; const float ss = wave_sum(v * v);
;             v = v * __builtin_amdgcn_rsqf(ss * (1.f / 64) + EPSN) * gg;
;             const float pv = __shfl_xor(v, 16);
;             const float o = up ? (pv * cs[1] + v * cs[0]) : (v * cs[0] - pv * cs[1]);
;             pr[base + lane] = tobf(o);
;         }
	v_add_f32_e32 v63, v63, v68
	v_cvt_pk_bf16_f32 v48, v60, s0
	global_store_short v[22:23], v43, off offset:3072
	global_store_short v[22:23], v48, off offset:3200
	v_mul_f32_e32 v43, v52, v52
	ds_bpermute_b32 v68, v36, v63
	ds_bpermute_b32 v43, v32, v43
	s_waitcnt lgkmcnt(3)
	v_add_f32_e32 v62, v62, v67
	v_fmamk_f32 v62, v62, 0x3c800000, v39
	s_waitcnt lgkmcnt(2)
	v_mul_f32_e32 v61, v45, v61
	v_rsq_f32_e32 v62, v62
	v_cndmask_b32_e64 v61, v61, -v61, s[4:5]
	v_fmac_f32_e32 v61, v44, v49
	v_cvt_pk_bf16_f32 v49, v61, s0
	s_waitcnt lgkmcnt(1)
	v_add_f32_e32 v48, v63, v68
	s_waitcnt lgkmcnt(0)
	v_fmac_f32_e32 v43, v52, v52
	global_store_short v[22:23], v49, off offset:3328
	ds_bpermute_b32 v49, v37, v48
	ds_bpermute_b32 v60, v33, v43
	v_mul_f32_e32 v50, v62, v50
	v_mul_f32_e32 v50, v42, v50
	ds_bpermute_b32 v62, v36, v50
	s_waitcnt lgkmcnt(2)
	v_add_f32_e32 v48, v48, v49
	s_waitcnt lgkmcnt(1)
	v_add_f32_e32 v43, v43, v60
	v_fmamk_f32 v48, v48, 0x3c800000, v39
	ds_bpermute_b32 v49, v34, v43
	v_rsq_f32_e32 v48, v48
	s_waitcnt lgkmcnt(1)
	v_mul_f32_e32 v57, v45, v62
	v_cndmask_b32_e64 v57, v57, -v57, s[4:5]
	v_lshlrev_b32_e32 v53, 16, v53
	v_fmac_f32_e32 v57, v44, v50
	v_cvt_pk_bf16_f32 v50, v57, s0
	v_mul_f32_e32 v48, v48, v51
	s_waitcnt lgkmcnt(0)
	v_add_f32_e32 v43, v43, v49
	v_mul_f32_e32 v57, v53, v53
	v_mul_f32_e32 v48, v42, v48
	ds_bpermute_b32 v49, v35, v43
	ds_bpermute_b32 v57, v32, v57
	ds_bpermute_b32 v51, v36, v48
	global_store_short v[22:23], v50, off offset:3456
	v_lshlrev_b32_e32 v54, 16, v54
	s_waitcnt lgkmcnt(2)
	v_add_f32_e32 v43, v43, v49
	s_waitcnt lgkmcnt(1)
	v_fmac_f32_e32 v57, v53, v53
	ds_bpermute_b32 v49, v36, v43
	s_waitcnt lgkmcnt(1)
	v_mul_f32_e32 v50, v45, v51
	ds_bpermute_b32 v51, v33, v57
	v_cndmask_b32_e64 v50, v50, -v50, s[4:5]
	v_fmac_f32_e32 v50, v44, v48
	s_waitcnt lgkmcnt(1)
	v_add_f32_e32 v43, v43, v49
	ds_bpermute_b32 v49, v37, v43
	s_waitcnt lgkmcnt(1)
	v_add_f32_e32 v48, v57, v51
	ds_bpermute_b32 v51, v34, v48
	v_cvt_pk_bf16_f32 v50, v50, s0
	global_store_short v[22:23], v50, off offset:3584
	v_mul_f32_e32 v50, v54, v54
	s_waitcnt lgkmcnt(1)
	v_add_f32_e32 v43, v43, v49
	s_waitcnt lgkmcnt(0)
	v_add_f32_e32 v48, v48, v51
	ds_bpermute_b32 v50, v32, v50
	v_fmamk_f32 v43, v43, 0x3c800000, v39
	ds_bpermute_b32 v49, v35, v48
	v_rsq_f32_e32 v43, v43
	v_lshlrev_b32_e32 v55, 16, v55
	s_waitcnt lgkmcnt(1)
	v_fmac_f32_e32 v50, v54, v54
	v_lshlrev_b32_e32 v56, 16, v56
	v_mul_f32_e32 v43, v43, v52
	s_waitcnt lgkmcnt(0)
	v_add_f32_e32 v48, v48, v49
	ds_bpermute_b32 v52, v33, v50
	ds_bpermute_b32 v49, v36, v48
	v_mul_f32_e32 v43, v42, v43
	ds_bpermute_b32 v51, v36, v43
	s_waitcnt lgkmcnt(2)
	v_add_f32_e32 v50, v50, v52
	s_waitcnt lgkmcnt(1)
	v_add_f32_e32 v48, v48, v49
	ds_bpermute_b32 v52, v34, v50
	ds_bpermute_b32 v49, v37, v48
	s_waitcnt lgkmcnt(2)
	v_mul_f32_e32 v51, v45, v51
	v_cndmask_b32_e64 v51, v51, -v51, s[4:5]
	v_fmac_f32_e32 v51, v44, v43
	s_waitcnt lgkmcnt(1)
	v_add_f32_e32 v43, v50, v52
	s_waitcnt lgkmcnt(0)
	v_add_f32_e32 v48, v48, v49
	ds_bpermute_b32 v49, v35, v43
	v_fmamk_f32 v48, v48, 0x3c800000, v39
	v_rsq_f32_e32 v48, v48
	v_cvt_pk_bf16_f32 v51, v51, s0
	global_store_short v[22:23], v51, off offset:3712
	s_waitcnt lgkmcnt(0)
	v_add_f32_e32 v43, v43, v49
	ds_bpermute_b32 v49, v36, v43
	v_mul_f32_e32 v48, v48, v53
	v_mul_f32_e32 v48, v42, v48
	ds_bpermute_b32 v50, v36, v48
	v_mul_f32_e32 v51, v55, v55
	s_waitcnt lgkmcnt(1)
	v_add_f32_e32 v43, v43, v49
	ds_bpermute_b32 v51, v32, v51
	ds_bpermute_b32 v49, v37, v43
	s_waitcnt lgkmcnt(2)
	v_mul_f32_e32 v50, v45, v50
	v_cndmask_b32_e64 v50, v50, -v50, s[4:5]
	v_fmac_f32_e32 v50, v44, v48
	s_waitcnt lgkmcnt(1)
	v_fmac_f32_e32 v51, v55, v55
	s_waitcnt lgkmcnt(0)
	v_add_f32_e32 v43, v43, v49
	v_mul_f32_e32 v49, v56, v56
	ds_bpermute_b32 v48, v33, v51
	ds_bpermute_b32 v49, v32, v49
	v_fmamk_f32 v43, v43, 0x3c800000, v39
	v_rsq_f32_e32 v43, v43
	v_cvt_pk_bf16_f32 v50, v50, s0
	s_waitcnt lgkmcnt(1)
	v_add_f32_e32 v48, v51, v48
	s_waitcnt lgkmcnt(0)
	v_fmac_f32_e32 v49, v56, v56
	ds_bpermute_b32 v51, v34, v48
	ds_bpermute_b32 v52, v33, v49
	v_mul_f32_e32 v43, v43, v54
	v_mul_f32_e32 v42, v42, v43
	global_store_short v[22:23], v50, off offset:3840
	s_waitcnt lgkmcnt(1)
; __device__ __forceinline__ unsigned cvtpk(float lo, float hi) { typedef __bf16 bf2 __attribute__((ext_vector_type(2))); f32x2 v = {lo, hi}; bf2 b = __builtin_convertvector(v, bf2); return __builtin_bit_cast(unsigned, b); }
; __device__ __forceinline__ bf16_t tobf(float f) { return (bf16_t)(cvtpk(f, 0.f) & 0xffffu); }
; __device__ __forceinline__ void prep_rows(bf16_t* proj, const float* gq, const float* gk, const float* mq, const float* mkv, const float* rope, int gw, int NGW, int lane) {
;     ...
;             const float pv = __shfl_xor(v, 16);
;             const float o = up ? (pv * cs[1] + v * cs[0]) : (v * cs[0] - pv * cs[1]);
;             pr[base + lane] = tobf(o);
;         }
;         {
;             const u32x2 w = *(const u32x2*)(pr + C_CQ + 4 * lane); f32x4 v = {bflo(w.x), bfhi(w.x), bflo(w.y), bfhi(w.y)};
;             const float rs = __builtin_amdgcn_rsqf(wave_sum((v[0] * v[0] + v[1] * v[1]) + (v[2] * v[2] + v[3] * v[3])) * (1.f / 256) + EPSN); const f32x4 gg = ((const f32x4*)mq)[lane];
;             u32x2 o; o.x = cvtpk(v[0] * rs * gg[0], v[1] * rs * gg[1]); o.y = cvtpk(v[2] * rs * gg[2], v[3] * rs * gg[3]); *(u32x2*)(pr + C_CQ + 4 * lane) = o;
;         }
;         {
;             const unsigned w = *(const unsigned*)(pr + C_CKV + 2 * lane); const float a = bflo(w), b = bfhi(w);
;             const float rs = __builtin_amdgcn_rsqf(wave_sum(a * a + b * b) * (1.f / 128) + EPSN); const f32x2 gg = ((const f32x2*)mkv)[lane];
;             *(unsigned*)(pr + C_CKV + 2 * lane) = cvtpk(a * rs * gg[0], b * rs * gg[1]);
;         }
;         {
;             const float v = bf1(pr[C_CKR + (lane & 31)]); const float pv = __shfl_xor(v, 16);
;             const f32x2 c2 = *(const f32x2*)(rope + ((size_t)l * 16 + j) * 2);
;             const float o = up ? (pv * c2[1] + v * c2[0]) : (v * c2[0] - pv * c2[1]);
;             if (lane < 32) pr[C_CKR + 2 * j + (lane >> 4)] = tobf(o);
	v_add_f32_e32 v48, v48, v51
	s_waitcnt lgkmcnt(0)
	v_add_f32_e32 v49, v49, v52
	ds_bpermute_b32 v51, v35, v48
	ds_bpermute_b32 v52, v34, v49
	s_waitcnt lgkmcnt(1)
	v_add_f32_e32 v43, v48, v51
	s_waitcnt lgkmcnt(0)
	v_add_f32_e32 v49, v49, v52
	ds_bpermute_b32 v48, v36, v43
	ds_bpermute_b32 v52, v35, v49
	ds_bpermute_b32 v51, v36, v42
	s_waitcnt lgkmcnt(2)
	v_add_f32_e32 v43, v43, v48
	s_waitcnt lgkmcnt(1)
	v_add_f32_e32 v49, v49, v52
	ds_bpermute_b32 v48, v37, v43
	s_waitcnt lgkmcnt(1)
	v_mul_f32_e32 v50, v45, v51
	ds_bpermute_b32 v51, v36, v49
	v_cndmask_b32_e64 v50, v50, -v50, s[4:5]
	v_fmac_f32_e32 v50, v44, v42
	s_waitcnt lgkmcnt(1)
	v_add_f32_e32 v43, v43, v48
	v_fmamk_f32 v43, v43, 0x3c800000, v39
	s_waitcnt lgkmcnt(0)
	v_add_f32_e32 v48, v49, v51
	ds_bpermute_b32 v49, v37, v48
	v_rsq_f32_e32 v43, v43
	s_waitcnt lgkmcnt(0)
	v_add_f32_e32 v48, v48, v49
	v_fmamk_f32 v48, v48, 0x3c800000, v39
	v_mul_f32_e32 v42, v43, v55
	v_rsq_f32_e32 v48, v48
	v_mul_f32_e32 v42, v41, v42
	ds_bpermute_b32 v43, v36, v42
	v_cvt_pk_bf16_f32 v49, v50, s0
	global_store_short v[22:23], v49, off offset:3968
	v_mul_f32_e32 v23, v48, v56
	v_mul_f32_e32 v23, v41, v23
	ds_bpermute_b32 v41, v36, v23
	s_waitcnt lgkmcnt(1)
	v_mul_f32_e32 v22, v45, v43
	v_cndmask_b32_e64 v22, v22, -v22, s[4:5]
	v_fmac_f32_e32 v22, v44, v42
	v_cvt_pk_bf16_f32 v22, v22, s0
	global_store_short v[24:25], v22, off
	s_waitcnt lgkmcnt(0)
	v_mul_f32_e32 v22, v45, v41
	v_cndmask_b32_e64 v22, v22, -v22, s[4:5]
	v_fmac_f32_e32 v22, v44, v23
	v_cvt_pk_bf16_f32 v22, v22, s0
	global_store_short v[24:25], v22, off offset:128
	v_and_b32_e32 v43, 0xffff0000, v47
	v_and_b32_e32 v45, 0xffff0000, v46
	v_lshlrev_b32_e32 v42, 16, v47
	v_lshlrev_b32_e32 v44, 16, v46
	v_mov_b32_e32 v48, v45
	v_mov_b32_e32 v49, v43
	v_mov_b32_e32 v46, v44
	v_mov_b32_e32 v47, v42
	v_pk_mul_f32 v[48:49], v[48:49], v[48:49]
	s_nop 0
	v_pk_fma_f32 v[46:47], v[46:47], v[46:47], v[48:49]
	s_nop 0
	v_add_f32_e32 v41, v46, v47
	ds_bpermute_b32 v46, v32, v41
	s_waitcnt lgkmcnt(0)
	v_add_f32_e32 v41, v41, v46
	ds_bpermute_b32 v46, v33, v41
	s_waitcnt lgkmcnt(0)
	v_add_f32_e32 v41, v41, v46
	ds_bpermute_b32 v46, v34, v41
	s_waitcnt lgkmcnt(0)
	v_add_f32_e32 v41, v41, v46
	ds_bpermute_b32 v46, v35, v41
	s_waitcnt lgkmcnt(0)
	v_add_f32_e32 v41, v41, v46
	ds_bpermute_b32 v46, v36, v41
	s_waitcnt lgkmcnt(0)
	v_add_f32_e32 v41, v41, v46
	ds_bpermute_b32 v46, v37, v41
	s_waitcnt lgkmcnt(0)
	v_add_f32_e32 v41, v41, v46
	v_fmamk_f32 v41, v41, 0x3b800000, v39
	v_rsq_f32_e32 v46, v41
	s_nop 0
	v_pk_mul_f32 v[44:45], v[46:47], v[44:45] op_sel_hi:[0,1]
	v_pk_mul_f32 v[42:43], v[46:47], v[42:43] op_sel_hi:[0,1]
	v_pk_mul_f32 v[22:23], v[124:125], v[44:45]
	v_pk_mul_f32 v[24:25], v[126:127], v[42:43]
	v_cvt_pk_bf16_f32 v22, v22, v23
	v_cvt_pk_bf16_f32 v23, v24, v25
	global_store_dwordx2 v[26:27], v[22:23], off
	v_lshlrev_b32_e32 v26, 16, v58
	v_and_b32_e32 v27, 0xffff0000, v58
	v_pk_mul_f32 v[22:23], v[26:27], v[26:27]
	s_nop 0
	v_add_f32_e32 v22, v22, v23
	ds_bpermute_b32 v23, v32, v22
	s_waitcnt lgkmcnt(0)
	v_add_f32_e32 v22, v22, v23
	ds_bpermute_b32 v23, v33, v22
	s_waitcnt lgkmcnt(0)
	v_add_f32_e32 v22, v22, v23
	ds_bpermute_b32 v23, v34, v22
	s_waitcnt lgkmcnt(0)
	v_add_f32_e32 v22, v22, v23
	ds_bpermute_b32 v23, v35, v22
	s_waitcnt lgkmcnt(0)
	v_add_f32_e32 v22, v22, v23
	ds_bpermute_b32 v23, v36, v22
	s_waitcnt lgkmcnt(0)
	v_add_f32_e32 v22, v22, v23
	ds_bpermute_b32 v23, v37, v22
	s_waitcnt lgkmcnt(0)
	v_add_f32_e32 v22, v22, v23
	v_fmamk_f32 v22, v22, 0x3c000000, v39
	v_rsq_f32_e32 v42, v22
	v_lshlrev_b32_e32 v22, 16, v59
	ds_bpermute_b32 v23, v36, v22
	v_pk_mul_f32 v[26:27], v[42:43], v[26:27] op_sel_hi:[0,1]
	v_pk_mul_f32 v[24:25], v[128:129], v[26:27]
	s_nop 0
	v_cvt_pk_bf16_f32 v24, v24, v25
	global_store_dword v[28:29], v24, off
	s_and_saveexec_b64 s[6:7], vcc
	s_cbranch_execz .LBB0_263
	v_lshl_add_u64 v[26:27], s[10:11], 0, v[16:17]
	s_waitcnt lgkmcnt(0)
	v_mul_f32_e32 v23, v121, v23
	v_cndmask_b32_e64 v23, v23, -v23, s[4:5]
	v_fmac_f32_e32 v23, v120, v22
	v_cvt_pk_bf16_f32 v22, v23, s0
	global_store_short v[26:27], v22, off
	s_branch .LBB0_263

; __device__ __forceinline__ unsigned cvtpk(float lo, float hi) { typedef __bf16 bf2 __attribute__((ext_vector_type(2))); f32x2 v = {lo, hi}; bf2 b = __builtin_convertvector(v, bf2); return __builtin_bit_cast(unsigned, b); }
; __device__ __forceinline__ bf16_t tobf(float f) { return (bf16_t)(cvtpk(f, 0.f) & 0xffffu); }
; __device__ __forceinline__ void prep_rows(bf16_t* proj, const float* gq, const float* gk, const float* mq, const float* mkv, const float* rope, int gw, int NGW, int lane) {
;     const int j = lane & 15; const bool up = (lane & 16) != 0;
;     for (int row = gw; row < NTOK; row += NGW) {
;         bf16_t* pr = proj + (size_t)row * LDP; const int l = row & (SEQL - 1); const int pos = (lane < 32) ? (l >> 6) : (l & 63);
;         const f32x2 cs = *(const f32x2*)(rope + ((size_t)pos * 16 + j) * 2);
;         float hv[10];
; #pragma unroll
;         for (int hh = 0; hh < 10; ++hh) hv[hh] = bf1(pr[(hh < 8 ? C_BQ + hh * 64 : C_BK + (hh - 8) * 64) + lane]);
;         const float ggq = gq[lane], ggk = gk[lane];
; #pragma unroll
;         for (int hh = 0; hh < 10; ++hh) {
;             const int base = hh < 8 ? C_BQ + hh * 64 : C_BK + (hh - 8) * 64; const float gg = hh < 8 ? ggq : ggk;
;             float v = hv[hh]; const float ss = wave_sum(v * v);
;             v = v * __builtin_amdgcn_rsqf(ss * (1.f / 64) + EPSN) * gg;
;             const float pv = __shfl_xor(v, 16);
;             const float o = up ? (pv * cs[1] + v * cs[0]) : (v * cs[0] - pv * cs[1]);
;             pr[base + lane] = tobf(o);
;         }
;         {
;             const u32x2 w = *(const u32x2*)(pr + C_CQ + 4 * lane); f32x4 v = {bflo(w.x), bfhi(w.x), bflo(w.y), bfhi(w.y)};
;             const float rs = __builtin_amdgcn_rsqf(wave_sum((v[0] * v[0] + v[1] * v[1]) + (v[2] * v[2] + v[3] * v[3])) * (1.f / 256) + EPSN); const f32x4 gg = ((const f32x4*)mq)[lane];
;             u32x2 o; o.x = cvtpk(v[0] * rs * gg[0], v[1] * rs * gg[1]); o.y = cvtpk(v[2] * rs * gg[2], v[3] * rs * gg[3]); *(u32x2*)(pr + C_CQ + 4 * lane) = o;
;         }
;         {
;             const unsigned w = *(const unsigned*)(pr + C_CKV + 2 * lane); const float a = bflo(w), b = bfhi(w);
;             const float rs = __builtin_amdgcn_rsqf(wave_sum(a * a + b * b) * (1.f / 128) + EPSN); const f32x2 gg = ((const f32x2*)mkv)[lane];
.LBB0_1688:
	s_cmp_lt_i32 s24, 13
	s_cselect_b64 s[4:5], -1, 0
	s_cmp_gt_i32 s25, 12
	s_cselect_b64 s[6:7], -1, 0
	s_and_b64 s[4:5], s[4:5], s[6:7]
	s_andn2_b64 vcc, exec, s[4:5]
	s_cbranch_vccnz .LBB0_1780
	s_mov_b64 s[34:35], s[0:1]
	s_waitcnt lgkmcnt(0)
	s_load_dwordx2 s[36:37], s[34:35], 0x118
	v_mov_b32_e32 v30, v1
	s_lshl_b32 s10, s33, 3
	v_readfirstlane_b32 s3, v30
	s_ashr_i32 s27, s3, 6
	v_and_b32_e32 v38, 63, v30
	s_add_i32 s3, s27, s10
	v_and_b32_e32 v31, 16, v30
	s_cmpk_gt_i32 s3, 0x3fff
	v_cmp_gt_u32_e32 vcc, 32, v38
	v_lshlrev_b32_e32 v2, 1, v38
	v_lshlrev_b32_e32 v4, 4, v38
	v_lshlrev_b32_e32 v40, 3, v38
	s_cbranch_scc1 .LBB0_1694
	v_mbcnt_lo_u32_b32 v3, -1, 0
	v_mbcnt_hi_u32_b32 v3, -1, v3
	v_and_b32_e32 v5, 64, v3
	v_add_u32_e32 v5, 64, v5
	v_xor_b32_e32 v12, 1, v3
	v_cmp_lt_i32_e64 s[6:7], v12, v5
	s_waitcnt lgkmcnt(0)
	s_add_u32 s8, s36, 0xf800000
	s_addc_u32 s9, s37, 0
	v_cndmask_b32_e64 v12, v3, v12, s[6:7]
	v_lshlrev_b32_e32 v32, 2, v12
	v_xor_b32_e32 v12, 2, v3
	v_cmp_lt_i32_e64 s[6:7], v12, v5
	s_load_dwordx8 s[16:23], s[34:35], 0x60
	v_mov_b32_e32 v7, 0
	v_cndmask_b32_e64 v12, v3, v12, s[6:7]
	v_lshlrev_b32_e32 v33, 2, v12
	v_xor_b32_e32 v12, 4, v3
	v_cmp_lt_i32_e64 s[6:7], v12, v5
	v_and_b32_e32 v22, 30, v2
	v_lshrrev_b32_e32 v16, 4, v38
	v_cndmask_b32_e64 v12, v3, v12, s[6:7]
	v_lshlrev_b32_e32 v34, 2, v12
	v_xor_b32_e32 v12, 8, v3
	v_cmp_lt_i32_e64 s[6:7], v12, v5
	v_lshlrev_b32_e32 v6, 2, v38
	v_mov_b32_e32 v41, v7
	v_cndmask_b32_e64 v12, v3, v12, s[6:7]
	v_lshlrev_b32_e32 v35, 2, v12
	v_xor_b32_e32 v12, 16, v3
	v_cmp_lt_i32_e64 s[6:7], v12, v5
	v_add_u32_e32 v16, v16, v22
	v_mov_b32_e32 v18, 0x1500
	v_cndmask_b32_e64 v12, v3, v12, s[6:7]
	v_lshlrev_b32_e32 v36, 2, v12
	v_xor_b32_e32 v12, 32, v3
	v_cmp_lt_i32_e64 s[6:7], v12, v5
	v_mov_b32_e32 v5, v7
	v_cmp_eq_u32_e64 s[4:5], 0, v31
	v_cndmask_b32_e64 v3, v3, v12, s[6:7]
	s_ashr_i32 s6, s27, 31
	s_ashr_i32 s7, s10, 31
	s_add_u32 s10, s27, s10
	s_addc_u32 s6, s6, s7
	s_mulk_i32 s6, 0x1940
	s_mul_hi_u32 s7, s10, 0x1940
	s_add_i32 s7, s7, s6
	s_mulk_i32 s10, 0x1940
	s_waitcnt lgkmcnt(0)
	v_lshl_add_u64 v[12:13], s[20:21], 0, v[4:5]
	v_and_b32_e32 v5, 31, v30
	s_add_u32 s10, s36, s10
	v_lshl_add_u64 v[8:9], s[16:17], 0, v[6:7]
	v_lshl_add_u64 v[10:11], s[18:19], 0, v[6:7]
	v_lshlrev_b32_e32 v37, 2, v3
	v_mov_b32_e32 v3, v7
	v_lshl_add_u64 v[14:15], s[22:23], 0, v[40:41]
	v_lshl_or_b32 v16, v16, 1, v18
	v_mov_b32_e32 v17, v7
	s_addc_u32 s11, s37, s7
	s_mul_hi_i32 s16, s26, 0x1940
	s_mul_i32 s17, s26, 0x1940
	v_lshl_or_b32 v18, v5, 1, v18
	v_mov_b32_e32 v19, v7
	v_or_b32_e32 v6, 0x1400, v6
	v_or_b32_e32 v20, 0x1200, v40
	v_mov_b32_e32 v21, v7
	v_lshlrev_b32_e32 v5, 2, v22
	s_movk_i32 s18, 0x1000
	v_mov_b32_e32 v39, 0x358637bd
	s_mov_b32 s19, s3
	global_load_dwordx4 v[124:127], v[12:13], off offset:1024
	global_load_dwordx2 v[128:129], v[14:15], off offset:512
	global_load_dword v148, v[8:9], off offset:256
	global_load_dword v149, v[10:11], off offset:256
	v_lshl_add_u64 v[150:151], s[10:11], 0, v[2:3]
	global_load_ushort v130, v[150:151], off offset:3072
	global_load_ushort v131, v[150:151], off offset:3200
	global_load_ushort v132, v[150:151], off offset:3328
	global_load_ushort v133, v[150:151], off offset:3456
	global_load_ushort v134, v[150:151], off offset:3584
	global_load_ushort v135, v[150:151], off offset:3712
	global_load_ushort v136, v[150:151], off offset:3840
	global_load_ushort v137, v[150:151], off offset:3968
	v_add_co_u32_e64 v152, s[6:7], s18, v150
	s_nop 0
	v_addc_co_u32_e64 v153, s[6:7], 0, v151, s[6:7]
	global_load_ushort v138, v[152:153], off
	global_load_ushort v139, v[152:153], off offset:128
	v_lshl_add_u64 v[152:153], s[10:11], 0, v[20:21]
	global_load_dwordx2 v[140:141], v[152:153], off
	v_lshl_add_u64 v[152:153], s[10:11], 0, v[6:7]
	global_load_dword v142, v[152:153], off
	v_lshl_add_u64 v[152:153], s[10:11], 0, v[18:19]
	global_load_ushort v143, v[152:153], off
	s_bfe_u32 s6, s19, 0x60006
	s_and_b32 s7, s19, 63
	v_mov_b32_e32 v152, s7
	v_mov_b32_e32 v153, s6
	v_cndmask_b32_e32 v152, v152, v153, vcc
	v_lshl_or_b32 v152, v152, 7, v5
	global_load_dwordx2 v[144:145], v152, s[8:9]
	s_and_saveexec_b64 s[98:99], vcc
	s_and_b32 s100, s19, 0xfff
	v_lshl_or_b32 v152, s100, 7, v5
	global_load_dwordx2 v[146:147], v152, s[8:9]
	s_or_b64 exec, exec, s[98:99]
	s_branch .LBB0_1692
